# last-unit write-through epilogues (out/ff1/ff2) + s_setprio removed from GEMM K-loops
# baseline (speedup 1.0000x reference)
.LBB0_1149:
	s_or_b64 exec, exec, s[34:35]
	s_waitcnt lgkmcnt(0)
	s_barrier
	ds_read_b32 v2, v2 offset:256
	s_mov_b32 s2, 0x800000
	v_lshl_add_u64 v[102:103], v[28:29], 0, s[26:27]
	v_mov_b32_e32 v89, v6
	v_mov_b32_e32 v104, v5
	s_waitcnt lgkmcnt(0)
	ds_bpermute_b32 v88, v149, v2
	v_mov_b32_e32 v105, v7
	s_addk_i32 s48, 0x80
	s_waitcnt lgkmcnt(0)
	v_add_f32_e32 v2, v2, v88
	ds_bpermute_b32 v88, v150, v2
	s_waitcnt lgkmcnt(0)
	v_add_f32_e32 v2, v2, v88
	ds_bpermute_b32 v106, v151, v2
	v_mov_b32_e32 v88, v4
	s_waitcnt lgkmcnt(0)
	v_add_f32_e32 v2, v2, v106
	s_nop 0
	v_readlane_b32 s7, v2, 0
	v_readlane_b32 s26, v2, 1
	v_readlane_b32 s27, v2, 2
	v_fma_f32 v106, s7, v206, v203
	v_mul_f32_e32 v107, 0x4b800000, v106
	v_cmp_gt_f32_e32 vcc, s2, v106
	v_readlane_b32 s28, v2, 3
	v_readlane_b32 s34, v2, 4
	v_cndmask_b32_e32 v106, v106, v107, vcc
	v_rsq_f32_e32 v106, v106
	v_readlane_b32 s35, v2, 5
	v_readlane_b32 s51, v2, 6
	v_readlane_b32 s7, v2, 7
	v_mul_f32_e32 v2, 0x45800000, v106
	v_cndmask_b32_e32 v2, v106, v2, vcc
	v_pk_mul_f32 v[72:73], v[72:73], v[2:3] op_sel_hi:[1,0]
	v_pk_mul_f32 v[12:13], v[12:13], v[2:3] op_sel_hi:[1,0]
	v_pk_fma_f32 v[72:73], v[52:53], v[72:73], v[88:89]
	v_pk_fma_f32 v[12:13], v[54:55], v[12:13], v[104:105]
	v_and_b32_sdwa v2, v73, v202 dst_sel:DWORD dst_unused:UNUSED_PAD src0_sel:WORD_1 src1_sel:DWORD
	v_and_b32_sdwa v106, v72, v202 dst_sel:DWORD dst_unused:UNUSED_PAD src0_sel:WORD_1 src1_sel:DWORD
	v_add3_u32 v2, v73, v2, s5
	v_and_b32_sdwa v73, v13, v202 dst_sel:DWORD dst_unused:UNUSED_PAD src0_sel:WORD_1 src1_sel:DWORD
	v_add3_u32 v72, v72, v106, s5
	v_and_b32_sdwa v106, v12, v202 dst_sel:DWORD dst_unused:UNUSED_PAD src0_sel:WORD_1 src1_sel:DWORD
	v_add3_u32 v13, v13, v73, s5
	v_fma_f32 v73, s26, v206, v203
	v_add3_u32 v12, v12, v106, s5
	v_mul_f32_e32 v106, 0x4b800000, v73
	v_cmp_gt_f32_e32 vcc, s2, v73
	v_and_b32_e32 v13, 0xffff0000, v13
	v_or_b32_sdwa v13, v13, v2 dst_sel:DWORD dst_unused:UNUSED_PAD src0_sel:DWORD src1_sel:WORD_1
	v_cndmask_b32_e32 v73, v73, v106, vcc
	v_rsq_f32_e32 v73, v73
	v_and_b32_e32 v12, 0xffff0000, v12
	v_or_b32_sdwa v12, v12, v72 dst_sel:DWORD dst_unused:UNUSED_PAD src0_sel:DWORD src1_sel:WORD_1
	global_store_dwordx2 v[102:103], v[12:13], off
	v_mul_f32_e32 v2, 0x45800000, v73
	v_cndmask_b32_e32 v2, v73, v2, vcc
	v_pk_mul_f32 v[72:73], v[74:75], v[2:3] op_sel_hi:[1,0]
	v_pk_mul_f32 v[74:75], v[76:77], v[2:3] op_sel_hi:[1,0]
	v_pk_fma_f32 v[72:73], v[52:53], v[72:73], v[88:89]
	v_pk_fma_f32 v[74:75], v[54:55], v[74:75], v[104:105]
	v_and_b32_sdwa v2, v73, v202 dst_sel:DWORD dst_unused:UNUSED_PAD src0_sel:WORD_1 src1_sel:DWORD
	v_and_b32_sdwa v76, v72, v202 dst_sel:DWORD dst_unused:UNUSED_PAD src0_sel:WORD_1 src1_sel:DWORD
	v_add3_u32 v2, v73, v2, s5
	v_and_b32_sdwa v73, v75, v202 dst_sel:DWORD dst_unused:UNUSED_PAD src0_sel:WORD_1 src1_sel:DWORD
	v_add3_u32 v72, v72, v76, s5
	v_and_b32_sdwa v76, v74, v202 dst_sel:DWORD dst_unused:UNUSED_PAD src0_sel:WORD_1 src1_sel:DWORD
	v_add3_u32 v73, v75, v73, s5
	v_fma_f32 v75, s27, v206, v203
	v_add3_u32 v74, v74, v76, s5
	v_mul_f32_e32 v76, 0x4b800000, v75
	v_cmp_gt_f32_e32 vcc, s2, v75
	v_and_b32_e32 v73, 0xffff0000, v73
	v_and_b32_e32 v74, 0xffff0000, v74
	v_cndmask_b32_e32 v75, v75, v76, vcc
	v_rsq_f32_e32 v75, v75
	v_or_b32_sdwa v73, v73, v2 dst_sel:DWORD dst_unused:UNUSED_PAD src0_sel:DWORD src1_sel:WORD_1
	v_lshl_add_u64 v[12:13], v[28:29], 0, s[24:25]
	v_or_b32_sdwa v72, v74, v72 dst_sel:DWORD dst_unused:UNUSED_PAD src0_sel:DWORD src1_sel:WORD_1
	v_mul_f32_e32 v2, 0x45800000, v75
	v_cndmask_b32_e32 v2, v75, v2, vcc
	global_store_dwordx2 v[12:13], v[72:73], off
	v_pk_mul_f32 v[72:73], v[78:79], v[2:3] op_sel_hi:[1,0]
	v_pk_mul_f32 v[74:75], v[80:81], v[2:3] op_sel_hi:[1,0]
	v_pk_fma_f32 v[72:73], v[52:53], v[72:73], v[88:89]
	v_pk_fma_f32 v[74:75], v[54:55], v[74:75], v[104:105]
	v_and_b32_sdwa v2, v73, v202 dst_sel:DWORD dst_unused:UNUSED_PAD src0_sel:WORD_1 src1_sel:DWORD
	v_and_b32_sdwa v76, v72, v202 dst_sel:DWORD dst_unused:UNUSED_PAD src0_sel:WORD_1 src1_sel:DWORD
	v_add3_u32 v2, v73, v2, s5
	v_and_b32_sdwa v73, v75, v202 dst_sel:DWORD dst_unused:UNUSED_PAD src0_sel:WORD_1 src1_sel:DWORD
	v_add3_u32 v72, v72, v76, s5
	v_and_b32_sdwa v76, v74, v202 dst_sel:DWORD dst_unused:UNUSED_PAD src0_sel:WORD_1 src1_sel:DWORD
	v_add3_u32 v73, v75, v73, s5
	v_fma_f32 v75, s28, v206, v203
	v_add3_u32 v74, v74, v76, s5
	v_mul_f32_e32 v76, 0x4b800000, v75
	v_cmp_gt_f32_e32 vcc, s2, v75
	v_and_b32_e32 v73, 0xffff0000, v73
	v_and_b32_e32 v74, 0xffff0000, v74
	v_cndmask_b32_e32 v75, v75, v76, vcc
	v_rsq_f32_e32 v75, v75
	v_or_b32_sdwa v73, v73, v2 dst_sel:DWORD dst_unused:UNUSED_PAD src0_sel:DWORD src1_sel:WORD_1
	v_lshl_add_u64 v[12:13], v[28:29], 0, s[20:21]
	v_or_b32_sdwa v72, v74, v72 dst_sel:DWORD dst_unused:UNUSED_PAD src0_sel:DWORD src1_sel:WORD_1
	v_mul_f32_e32 v2, 0x45800000, v75
	v_cndmask_b32_e32 v2, v75, v2, vcc
	global_store_dwordx2 v[12:13], v[72:73], off
	v_pk_mul_f32 v[72:73], v[82:83], v[2:3] op_sel_hi:[1,0]
	v_pk_mul_f32 v[74:75], v[84:85], v[2:3] op_sel_hi:[1,0]
	v_pk_fma_f32 v[72:73], v[52:53], v[72:73], v[88:89]
	v_pk_fma_f32 v[74:75], v[54:55], v[74:75], v[104:105]
	v_and_b32_sdwa v2, v73, v202 dst_sel:DWORD dst_unused:UNUSED_PAD src0_sel:WORD_1 src1_sel:DWORD
	v_and_b32_sdwa v76, v72, v202 dst_sel:DWORD dst_unused:UNUSED_PAD src0_sel:WORD_1 src1_sel:DWORD
	v_add3_u32 v2, v73, v2, s5
	v_and_b32_sdwa v73, v75, v202 dst_sel:DWORD dst_unused:UNUSED_PAD src0_sel:WORD_1 src1_sel:DWORD
	v_add3_u32 v72, v72, v76, s5
	v_and_b32_sdwa v76, v74, v202 dst_sel:DWORD dst_unused:UNUSED_PAD src0_sel:WORD_1 src1_sel:DWORD
	v_add3_u32 v73, v75, v73, s5
	v_fma_f32 v75, s34, v206, v203
	v_add3_u32 v74, v74, v76, s5
	v_mul_f32_e32 v76, 0x4b800000, v75
	v_cmp_gt_f32_e32 vcc, s2, v75
	v_and_b32_e32 v73, 0xffff0000, v73
	v_and_b32_e32 v74, 0xffff0000, v74
	v_cndmask_b32_e32 v75, v75, v76, vcc
	v_rsq_f32_e32 v75, v75
	v_or_b32_sdwa v73, v73, v2 dst_sel:DWORD dst_unused:UNUSED_PAD src0_sel:DWORD src1_sel:WORD_1
	v_lshl_add_u64 v[12:13], v[28:29], 0, s[18:19]
	v_or_b32_sdwa v72, v74, v72 dst_sel:DWORD dst_unused:UNUSED_PAD src0_sel:DWORD src1_sel:WORD_1
	v_mul_f32_e32 v2, 0x45800000, v75
	v_cndmask_b32_e32 v2, v75, v2, vcc
	global_store_dwordx2 v[12:13], v[72:73], off
	v_pk_mul_f32 v[72:73], v[86:87], v[2:3] op_sel_hi:[1,0]
	v_pk_mul_f32 v[74:75], v[96:97], v[2:3] op_sel_hi:[1,0]
	v_pk_fma_f32 v[72:73], v[52:53], v[72:73], v[88:89]
	v_pk_fma_f32 v[74:75], v[54:55], v[74:75], v[104:105]
	v_and_b32_sdwa v2, v73, v202 dst_sel:DWORD dst_unused:UNUSED_PAD src0_sel:WORD_1 src1_sel:DWORD
	v_and_b32_sdwa v76, v72, v202 dst_sel:DWORD dst_unused:UNUSED_PAD src0_sel:WORD_1 src1_sel:DWORD
	v_add3_u32 v2, v73, v2, s5
	v_and_b32_sdwa v73, v75, v202 dst_sel:DWORD dst_unused:UNUSED_PAD src0_sel:WORD_1 src1_sel:DWORD
	v_add3_u32 v72, v72, v76, s5
	v_and_b32_sdwa v76, v74, v202 dst_sel:DWORD dst_unused:UNUSED_PAD src0_sel:WORD_1 src1_sel:DWORD
	v_add3_u32 v73, v75, v73, s5
	v_fma_f32 v75, s35, v206, v203
	v_add3_u32 v74, v74, v76, s5
	v_mul_f32_e32 v76, 0x4b800000, v75
	v_cmp_gt_f32_e32 vcc, s2, v75
	v_and_b32_e32 v73, 0xffff0000, v73
	v_and_b32_e32 v74, 0xffff0000, v74
	v_cndmask_b32_e32 v75, v75, v76, vcc
	v_rsq_f32_e32 v75, v75
	v_or_b32_sdwa v73, v73, v2 dst_sel:DWORD dst_unused:UNUSED_PAD src0_sel:DWORD src1_sel:WORD_1
	v_lshl_add_u64 v[12:13], v[28:29], 0, s[16:17]
	v_or_b32_sdwa v72, v74, v72 dst_sel:DWORD dst_unused:UNUSED_PAD src0_sel:DWORD src1_sel:WORD_1
	v_mul_f32_e32 v2, 0x45800000, v75
	v_cndmask_b32_e32 v2, v75, v2, vcc
	global_store_dwordx2 v[12:13], v[72:73], off
	v_pk_mul_f32 v[72:73], v[100:101], v[2:3] op_sel_hi:[1,0]
	v_pk_mul_f32 v[74:75], v[94:95], v[2:3] op_sel_hi:[1,0]
	v_pk_fma_f32 v[72:73], v[52:53], v[72:73], v[88:89]
	v_pk_fma_f32 v[74:75], v[54:55], v[74:75], v[104:105]
	v_and_b32_sdwa v2, v73, v202 dst_sel:DWORD dst_unused:UNUSED_PAD src0_sel:WORD_1 src1_sel:DWORD
	v_and_b32_sdwa v76, v72, v202 dst_sel:DWORD dst_unused:UNUSED_PAD src0_sel:WORD_1 src1_sel:DWORD
	v_add3_u32 v2, v73, v2, s5
	v_and_b32_sdwa v73, v75, v202 dst_sel:DWORD dst_unused:UNUSED_PAD src0_sel:WORD_1 src1_sel:DWORD
	v_add3_u32 v72, v72, v76, s5
	v_and_b32_sdwa v76, v74, v202 dst_sel:DWORD dst_unused:UNUSED_PAD src0_sel:WORD_1 src1_sel:DWORD
	v_add3_u32 v73, v75, v73, s5
	v_fma_f32 v75, s51, v206, v203
	v_add3_u32 v74, v74, v76, s5
	v_mul_f32_e32 v76, 0x4b800000, v75
	v_cmp_gt_f32_e32 vcc, s2, v75
	v_and_b32_e32 v73, 0xffff0000, v73
	v_and_b32_e32 v74, 0xffff0000, v74
	v_cndmask_b32_e32 v75, v75, v76, vcc
	v_rsq_f32_e32 v75, v75
	v_or_b32_sdwa v73, v73, v2 dst_sel:DWORD dst_unused:UNUSED_PAD src0_sel:DWORD src1_sel:WORD_1
	v_lshl_add_u64 v[12:13], v[28:29], 0, s[14:15]
	v_or_b32_sdwa v72, v74, v72 dst_sel:DWORD dst_unused:UNUSED_PAD src0_sel:DWORD src1_sel:WORD_1
	v_mul_f32_e32 v2, 0x45800000, v75
	v_cndmask_b32_e32 v2, v75, v2, vcc
	global_store_dwordx2 v[12:13], v[72:73], off
	v_pk_mul_f32 v[72:73], v[98:99], v[2:3] op_sel_hi:[1,0]
	v_pk_mul_f32 v[74:75], v[90:91], v[2:3] op_sel_hi:[1,0]
	v_pk_fma_f32 v[72:73], v[52:53], v[72:73], v[88:89]
	v_pk_fma_f32 v[74:75], v[54:55], v[74:75], v[104:105]
	v_and_b32_sdwa v2, v73, v202 dst_sel:DWORD dst_unused:UNUSED_PAD src0_sel:WORD_1 src1_sel:DWORD
	v_and_b32_sdwa v76, v72, v202 dst_sel:DWORD dst_unused:UNUSED_PAD src0_sel:WORD_1 src1_sel:DWORD
	v_add3_u32 v2, v73, v2, s5
	v_and_b32_sdwa v73, v75, v202 dst_sel:DWORD dst_unused:UNUSED_PAD src0_sel:WORD_1 src1_sel:DWORD
	v_add3_u32 v72, v72, v76, s5
	v_and_b32_sdwa v76, v74, v202 dst_sel:DWORD dst_unused:UNUSED_PAD src0_sel:WORD_1 src1_sel:DWORD
	v_add3_u32 v73, v75, v73, s5
	v_fma_f32 v75, s7, v206, v203
	v_add3_u32 v74, v74, v76, s5
	v_mul_f32_e32 v76, 0x4b800000, v75
	v_cmp_gt_f32_e32 vcc, s2, v75
	v_and_b32_e32 v73, 0xffff0000, v73
	v_and_b32_e32 v74, 0xffff0000, v74
	v_cndmask_b32_e32 v75, v75, v76, vcc
	v_rsq_f32_e32 v75, v75
	v_or_b32_sdwa v73, v73, v2 dst_sel:DWORD dst_unused:UNUSED_PAD src0_sel:DWORD src1_sel:WORD_1
	v_lshl_add_u64 v[12:13], v[28:29], 0, s[12:13]
	v_or_b32_sdwa v72, v74, v72 dst_sel:DWORD dst_unused:UNUSED_PAD src0_sel:DWORD src1_sel:WORD_1
	v_mul_f32_e32 v2, 0x45800000, v75
	v_cndmask_b32_e32 v2, v75, v2, vcc
	global_store_dwordx2 v[12:13], v[72:73], off
	v_pk_mul_f32 v[72:73], v[92:93], v[2:3] op_sel_hi:[1,0]
	v_pk_mul_f32 v[14:15], v[14:15], v[2:3] op_sel_hi:[1,0]
	v_pk_fma_f32 v[72:73], v[52:53], v[72:73], v[88:89]
	v_pk_fma_f32 v[14:15], v[54:55], v[14:15], v[104:105]
	v_and_b32_sdwa v2, v73, v202 dst_sel:DWORD dst_unused:UNUSED_PAD src0_sel:WORD_1 src1_sel:DWORD
	v_and_b32_sdwa v74, v72, v202 dst_sel:DWORD dst_unused:UNUSED_PAD src0_sel:WORD_1 src1_sel:DWORD
	v_add3_u32 v72, v72, v74, s5
	v_add3_u32 v2, v73, v2, s5
	v_and_b32_sdwa v73, v15, v202 dst_sel:DWORD dst_unused:UNUSED_PAD src0_sel:WORD_1 src1_sel:DWORD
	v_and_b32_sdwa v74, v14, v202 dst_sel:DWORD dst_unused:UNUSED_PAD src0_sel:WORD_1 src1_sel:DWORD
	v_add3_u32 v15, v15, v73, s5
	v_add3_u32 v14, v14, v74, s5
	v_and_b32_e32 v15, 0xffff0000, v15
	v_and_b32_e32 v14, 0xffff0000, v14
	v_readlane_b32 s2, v250, 47
	v_lshl_add_u64 v[12:13], v[28:29], 0, s[10:11]
	v_or_b32_sdwa v15, v15, v2 dst_sel:DWORD dst_unused:UNUSED_PAD src0_sel:DWORD src1_sel:WORD_1
	v_or_b32_sdwa v14, v14, v72 dst_sel:DWORD dst_unused:UNUSED_PAD src0_sel:DWORD src1_sel:WORD_1
	s_add_i32 s6, s6, s2
	s_andn2_b64 vcc, exec, s[8:9]
	v_mov_b64_e32 v[72:73], v[44:45]
	v_mov_b64_e32 v[76:77], v[46:47]
	v_mov_b64_e32 v[78:79], v[48:49]
	v_mov_b64_e32 v[82:83], v[50:51]
	v_mov_b64_e32 v[74:75], v[36:37]
	v_mov_b64_e32 v[80:81], v[38:39]
	v_mov_b64_e32 v[84:85], v[40:41]
	v_mov_b64_e32 v[86:87], v[42:43]
	v_mov_b64_e32 v[88:89], v[64:65]
	v_mov_b64_e32 v[92:93], v[66:67]
	v_mov_b64_e32 v[98:99], v[68:69]
	v_mov_b64_e32 v[102:103], v[70:71]
	v_mov_b64_e32 v[90:91], v[56:57]
	v_mov_b64_e32 v[94:95], v[58:59]
	v_mov_b64_e32 v[96:97], v[60:61]
	v_mov_b64_e32 v[100:101], v[62:63]
	s_mov_b32 s7, s50
	global_store_dwordx2 v[12:13], v[14:15], off
	s_cbranch_vccz .LBB0_1160

.LBB0_1154:
	v_readlane_b32 s2, v250, 19
	s_cmpk_lt_i32 s7, 0x400
	v_readlane_b32 s3, v250, 20
	s_cselect_b64 s[10:11], -1, 0
	s_xor_b64 s[12:13], s[2:3], -1
	s_or_b64 s[10:11], s[12:13], s[10:11]
	s_waitcnt vmcnt(7)
	v_lshlrev_b32_e32 v118, 16, v100
	v_and_b32_e32 v110, 0xffff0000, v100
	v_lshlrev_b32_e32 v119, 16, v101
	v_and_b32_e32 v111, 0xffff0000, v101
	s_waitcnt vmcnt(6)
	v_lshlrev_b32_e32 v116, 16, v96
	v_and_b32_e32 v106, 0xffff0000, v96
	v_lshlrev_b32_e32 v117, 16, v97
	v_and_b32_e32 v107, 0xffff0000, v97
	s_waitcnt vmcnt(5)
	v_lshlrev_b32_e32 v114, 16, v94
	v_and_b32_e32 v104, 0xffff0000, v94
	v_lshlrev_b32_e32 v115, 16, v95
	v_and_b32_e32 v105, 0xffff0000, v95
	s_waitcnt vmcnt(4)
	v_lshlrev_b32_e32 v112, 16, v90
	v_and_b32_e32 v100, 0xffff0000, v90
	v_lshlrev_b32_e32 v113, 16, v91
	v_and_b32_e32 v101, 0xffff0000, v91
	s_waitcnt vmcnt(3)
	v_lshlrev_b32_e32 v108, 16, v102
	v_and_b32_e32 v96, 0xffff0000, v102
	v_lshlrev_b32_e32 v109, 16, v103
	v_and_b32_e32 v97, 0xffff0000, v103
	s_waitcnt vmcnt(2)
	v_lshlrev_b32_e32 v102, 16, v98
	v_and_b32_e32 v94, 0xffff0000, v98
	v_lshlrev_b32_e32 v103, 16, v99
	v_and_b32_e32 v95, 0xffff0000, v99
	s_waitcnt vmcnt(1)
	v_lshlrev_b32_e32 v98, 16, v92
	v_and_b32_e32 v90, 0xffff0000, v92
	v_lshlrev_b32_e32 v99, 16, v93
	v_and_b32_e32 v91, 0xffff0000, v93
	s_waitcnt vmcnt(0)
	v_lshlrev_b32_e32 v92, 16, v88
	v_and_b32_e32 v88, 0xffff0000, v88
	v_lshlrev_b32_e32 v93, 16, v89
	v_and_b32_e32 v89, 0xffff0000, v89
	s_and_b64 vcc, exec, s[10:11]
	s_cbranch_vccnz .LBB0_1156
	s_add_i32 s28, s6, 1
	s_lshl_b64 s[12:13], s[28:29], 12
	s_add_i32 s28, s6, 2
	s_lshl_b64 s[14:15], s[28:29], 12
	s_add_i32 s28, s6, 3
	s_lshl_b64 s[18:19], s[28:29], 12
	s_add_i32 s28, s6, 4
	s_lshl_b64 s[16:17], s[28:29], 12
	s_add_i32 s28, s6, 5
	s_mov_b32 s7, s29
	s_lshl_b64 s[20:21], s[28:29], 12
	s_add_i32 s28, s6, 6
	s_lshl_b64 s[10:11], s[6:7], 12
	s_lshl_b64 s[24:25], s[28:29], 12
	s_add_i32 s28, s6, 7
	v_lshl_add_u64 v[120:121], v[30:31], 0, s[10:11]
	v_lshl_add_u64 v[134:135], v[30:31], 0, s[24:25]
	s_lshl_b64 s[26:27], s[28:29], 12
	v_lshl_add_u64 v[144:145], v[32:33], 0, s[18:19]
	global_load_dwordx2 v[122:123], v[120:121], off
	v_lshl_add_u64 v[136:137], v[30:31], 0, s[26:27]
	global_load_dwordx2 v[134:135], v[134:135], off
	v_lshl_add_u64 v[154:155], v[32:33], 0, s[20:21]
	global_load_dwordx2 v[144:145], v[144:145], off
	v_lshl_add_u64 v[120:121], v[30:31], 0, s[12:13]
	global_load_dwordx2 v[124:125], v[120:121], off
	v_lshl_add_u64 v[138:139], v[32:33], 0, s[10:11]
	global_load_dwordx2 v[136:137], v[136:137], off
	v_lshl_add_u64 v[156:157], v[32:33], 0, s[24:25]
	global_load_dwordx2 v[154:155], v[154:155], off
	v_lshl_add_u64 v[120:121], v[30:31], 0, s[14:15]
	global_load_dwordx2 v[126:127], v[120:121], off
	v_lshl_add_u64 v[130:131], v[30:31], 0, s[16:17]
	v_lshl_add_u64 v[132:133], v[30:31], 0, s[20:21]
	global_load_dwordx2 v[138:139], v[138:139], off
	v_lshl_add_u64 v[142:143], v[32:33], 0, s[14:15]
	global_load_dwordx2 v[156:157], v[156:157], off
	v_mov_b32_e32 v120, v118
	v_mov_b32_e32 v121, v110
	v_mov_b32_e32 v110, v119
	v_lshl_add_u64 v[118:119], v[30:31], 0, s[18:19]
	v_lshl_add_u64 v[160:161], v[34:35], 0, s[10:11]
	global_load_dwordx2 v[128:129], v[118:119], off
	v_mov_b32_e32 v140, v112
	global_load_dwordx2 v[130:131], v[130:131], off
	v_mov_b32_e32 v141, v100
	global_load_dwordx2 v[132:133], v[132:133], off
	v_mov_b32_e32 v100, v113
	global_load_dwordx2 v[142:143], v[142:143], off
	v_mov_b32_e32 v112, v108
	v_mov_b32_e32 v113, v96
	v_mov_b32_e32 v96, v109
	v_lshl_add_u64 v[108:109], v[32:33], 0, s[16:17]
	v_mov_b32_e32 v152, v102
	v_mov_b32_e32 v153, v94
	v_mov_b32_e32 v94, v103
	v_mov_b32_e32 v102, v98
	v_mov_b32_e32 v103, v90
	v_mov_b32_e32 v90, v99
	v_lshl_add_u64 v[98:99], v[32:33], 0, s[26:27]
	global_load_dwordx2 v[160:161], v[160:161], off
	v_mov_b32_e32 v118, v116
	v_mov_b32_e32 v119, v106
	v_mov_b32_e32 v106, v117
	v_mov_b32_e32 v116, v114
	v_mov_b32_e32 v117, v104
	v_mov_b32_e32 v104, v115
	v_lshl_add_u64 v[114:115], v[32:33], 0, s[12:13]
	global_load_dwordx2 v[114:115], v[114:115], off
	v_mov_b32_e32 v158, v92
	global_load_dwordx2 v[108:109], v[108:109], off
	v_mov_b32_e32 v159, v88
	global_load_dwordx2 v[98:99], v[98:99], off
	v_mov_b32_e32 v88, v93
	v_lshl_add_u64 v[92:93], v[34:35], 0, s[12:13]
	v_lshl_add_u64 v[162:163], v[34:35], 0, s[14:15]
	v_lshl_add_u64 v[164:165], v[34:35], 0, s[18:19]
	v_lshl_add_u64 v[182:183], v[34:35], 0, s[16:17]
	v_lshl_add_u64 v[186:187], v[34:35], 0, s[20:21]
	v_lshl_add_u64 v[188:189], v[34:35], 0, s[24:25]
	v_lshl_add_u64 v[192:193], v[34:35], 0, s[26:27]
	global_load_dwordx2 v[92:93], v[92:93], off
	s_nop 0
	global_load_dwordx2 v[162:163], v[162:163], off
	s_waitcnt vmcnt(18)
	v_lshlrev_b32_e32 v166, 16, v122
	global_load_dwordx2 v[164:165], v[164:165], off
	v_and_b32_e32 v167, 0xffff0000, v122
	global_load_dwordx2 v[182:183], v[182:183], off
	v_lshlrev_b32_e32 v122, 16, v123
	global_load_dwordx2 v[186:187], v[186:187], off
	v_and_b32_e32 v123, 0xffff0000, v123
	global_load_dwordx2 v[188:189], v[188:189], off
	s_waitcnt vmcnt(19)
	v_lshlrev_b32_e32 v180, 16, v124
	global_load_dwordx2 v[192:193], v[192:193], off
	v_and_b32_e32 v181, 0xffff0000, v124
	v_lshlrev_b32_e32 v124, 16, v125
	v_and_b32_e32 v125, 0xffff0000, v125
	s_waitcnt vmcnt(17)
	v_lshlrev_b32_e32 v184, 16, v126
	v_and_b32_e32 v185, 0xffff0000, v126
	v_lshlrev_b32_e32 v126, 16, v127
	v_and_b32_e32 v127, 0xffff0000, v127
	v_lshlrev_b32_e32 v198, 16, v134
	v_and_b32_e32 v199, 0xffff0000, v134
	v_lshlrev_b32_e32 v134, 16, v135
	v_and_b32_e32 v135, 0xffff0000, v135
	v_lshlrev_b32_e32 v208, 16, v136
	v_and_b32_e32 v209, 0xffff0000, v136
	s_waitcnt vmcnt(14)
	v_lshlrev_b32_e32 v190, 16, v128
	v_and_b32_e32 v191, 0xffff0000, v128
	v_lshlrev_b32_e32 v128, 16, v129
	v_and_b32_e32 v129, 0xffff0000, v129
	s_waitcnt vmcnt(13)
	v_lshlrev_b32_e32 v194, 16, v130
	v_and_b32_e32 v195, 0xffff0000, v130
	v_lshlrev_b32_e32 v130, 16, v131
	v_and_b32_e32 v131, 0xffff0000, v131
	s_waitcnt vmcnt(12)
	v_lshlrev_b32_e32 v196, 16, v132
	v_and_b32_e32 v197, 0xffff0000, v132
	v_lshlrev_b32_e32 v132, 16, v133
	v_and_b32_e32 v133, 0xffff0000, v133
	v_lshlrev_b32_e32 v136, 16, v137
	v_and_b32_e32 v137, 0xffff0000, v137
	v_lshlrev_b32_e32 v210, 16, v138
	v_and_b32_e32 v211, 0xffff0000, v138
	v_lshlrev_b32_e32 v138, 16, v139
	v_and_b32_e32 v139, 0xffff0000, v139
	s_waitcnt vmcnt(11)
	v_lshlrev_b32_e32 v214, 16, v142
	v_and_b32_e32 v215, 0xffff0000, v142
	v_lshlrev_b32_e32 v142, 16, v143
	v_and_b32_e32 v143, 0xffff0000, v143
	v_lshlrev_b32_e32 v216, 16, v144
	v_and_b32_e32 v217, 0xffff0000, v144
	v_lshlrev_b32_e32 v144, 16, v145
	v_and_b32_e32 v145, 0xffff0000, v145
	s_waitcnt vmcnt(9)
	v_lshlrev_b32_e32 v212, 16, v114
	v_and_b32_e32 v213, 0xffff0000, v114
	v_lshlrev_b32_e32 v114, 16, v115
	v_and_b32_e32 v115, 0xffff0000, v115
	s_waitcnt vmcnt(8)
	v_lshlrev_b32_e32 v218, 16, v108
	v_and_b32_e32 v219, 0xffff0000, v108
	v_lshlrev_b32_e32 v108, 16, v109
	v_and_b32_e32 v109, 0xffff0000, v109
	v_lshlrev_b32_e32 v220, 16, v154
	v_and_b32_e32 v221, 0xffff0000, v154
	v_lshlrev_b32_e32 v154, 16, v155
	v_and_b32_e32 v155, 0xffff0000, v155
	v_lshlrev_b32_e32 v222, 16, v156
	v_and_b32_e32 v223, 0xffff0000, v156
	v_lshlrev_b32_e32 v156, 16, v157
	v_and_b32_e32 v157, 0xffff0000, v157
	s_waitcnt vmcnt(7)
	v_lshlrev_b32_e32 v224, 16, v98
	v_and_b32_e32 v225, 0xffff0000, v98
	v_lshlrev_b32_e32 v98, 16, v99
	v_and_b32_e32 v99, 0xffff0000, v99
	v_pk_add_f32 v[88:89], v[88:89], v[136:137]
	v_pk_add_f32 v[136:137], v[158:159], v[208:209]
	v_pk_add_f32 v[90:91], v[90:91], v[134:135]
	v_pk_add_f32 v[102:103], v[102:103], v[198:199]
	v_pk_add_f32 v[94:95], v[94:95], v[132:133]
	v_pk_add_f32 v[132:133], v[152:153], v[196:197]
	v_pk_add_f32 v[96:97], v[96:97], v[130:131]
	v_pk_add_f32 v[112:113], v[112:113], v[194:195]
	v_pk_add_f32 v[100:101], v[100:101], v[128:129]
	v_pk_add_f32 v[128:129], v[140:141], v[190:191]
	v_pk_add_f32 v[104:105], v[104:105], v[126:127]
	v_pk_add_f32 v[116:117], v[116:117], v[184:185]
	v_pk_add_f32 v[106:107], v[106:107], v[124:125]
	v_pk_add_f32 v[118:119], v[118:119], v[180:181]
	v_pk_add_f32 v[110:111], v[110:111], v[122:123]
	v_pk_add_f32 v[120:121], v[120:121], v[166:167]
	v_lshlrev_b32_e32 v226, 16, v160
	v_and_b32_e32 v227, 0xffff0000, v160
	v_lshlrev_b32_e32 v160, 16, v161
	v_and_b32_e32 v161, 0xffff0000, v161
	s_waitcnt vmcnt(6)
	v_lshlrev_b32_e32 v228, 16, v92
	v_and_b32_e32 v229, 0xffff0000, v92
	v_lshlrev_b32_e32 v230, 16, v93
	v_and_b32_e32 v231, 0xffff0000, v93
	s_waitcnt vmcnt(5)
	v_lshlrev_b32_e32 v232, 16, v162
	v_and_b32_e32 v233, 0xffff0000, v162
	v_lshlrev_b32_e32 v162, 16, v163
	v_and_b32_e32 v163, 0xffff0000, v163
	s_waitcnt vmcnt(4)
	v_lshlrev_b32_e32 v234, 16, v164
	v_and_b32_e32 v235, 0xffff0000, v164
	v_lshlrev_b32_e32 v164, 16, v165
	v_and_b32_e32 v165, 0xffff0000, v165
	s_waitcnt vmcnt(3)
	v_lshlrev_b32_e32 v236, 16, v182
	v_and_b32_e32 v237, 0xffff0000, v182
	v_lshlrev_b32_e32 v182, 16, v183
	v_and_b32_e32 v183, 0xffff0000, v183
	s_waitcnt vmcnt(2)
	v_lshlrev_b32_e32 v238, 16, v186
	v_and_b32_e32 v239, 0xffff0000, v186
	v_lshlrev_b32_e32 v186, 16, v187
	v_and_b32_e32 v187, 0xffff0000, v187
	s_waitcnt vmcnt(1)
	v_lshlrev_b32_e32 v240, 16, v188
	v_and_b32_e32 v241, 0xffff0000, v188
	v_lshlrev_b32_e32 v188, 16, v189
	v_and_b32_e32 v189, 0xffff0000, v189
	s_waitcnt vmcnt(0)
	v_lshlrev_b32_e32 v92, 16, v192
	v_and_b32_e32 v93, 0xffff0000, v192
	v_lshlrev_b32_e32 v192, 16, v193
	v_and_b32_e32 v193, 0xffff0000, v193
	v_pk_add_f32 v[120:121], v[120:121], v[210:211]
	v_pk_add_f32 v[110:111], v[110:111], v[138:139]
	v_pk_add_f32 v[118:119], v[118:119], v[212:213]
	v_pk_add_f32 v[106:107], v[106:107], v[114:115]
	v_pk_add_f32 v[114:115], v[116:117], v[214:215]
	v_pk_add_f32 v[104:105], v[104:105], v[142:143]
	v_pk_add_f32 v[116:117], v[128:129], v[216:217]
	v_pk_add_f32 v[100:101], v[100:101], v[144:145]
	v_pk_add_f32 v[112:113], v[112:113], v[218:219]
	v_pk_add_f32 v[96:97], v[96:97], v[108:109]
	v_pk_add_f32 v[108:109], v[132:133], v[220:221]
	v_pk_add_f32 v[94:95], v[94:95], v[154:155]
	v_pk_add_f32 v[102:103], v[102:103], v[222:223]
	v_pk_add_f32 v[90:91], v[90:91], v[156:157]
	v_pk_add_f32 v[122:123], v[136:137], v[224:225]
	v_pk_add_f32 v[88:89], v[88:89], v[98:99]
	v_pk_add_f32 v[92:93], v[122:123], v[92:93]
	v_pk_add_f32 v[124:125], v[88:89], v[192:193]
	v_pk_add_f32 v[88:89], v[90:91], v[188:189]
	v_pk_add_f32 v[98:99], v[102:103], v[240:241]
	v_pk_add_f32 v[90:91], v[94:95], v[186:187]
	v_pk_add_f32 v[102:103], v[108:109], v[238:239]
	v_pk_add_f32 v[94:95], v[96:97], v[182:183]
	v_pk_add_f32 v[108:109], v[112:113], v[236:237]
	v_pk_add_f32 v[96:97], v[100:101], v[164:165]
	v_pk_add_f32 v[112:113], v[116:117], v[234:235]
	v_pk_add_f32 v[100:101], v[104:105], v[162:163]
	v_pk_add_f32 v[114:115], v[114:115], v[232:233]
	v_pk_add_f32 v[104:105], v[106:107], v[230:231]
	v_pk_add_f32 v[116:117], v[118:119], v[228:229]
	v_pk_add_f32 v[106:107], v[110:111], v[160:161]
	v_pk_add_f32 v[118:119], v[120:121], v[226:227]
	v_mov_b32_e32 v111, v107
	v_mov_b32_e32 v110, v119
	v_mov_b32_e32 v119, v106
	v_mov_b32_e32 v106, v117
	v_mov_b32_e32 v117, v104
	v_mov_b32_e32 v107, v105
	v_mov_b32_e32 v104, v115
	v_mov_b32_e32 v115, v100
	v_mov_b32_e32 v105, v101
	v_mov_b32_e32 v100, v113
	v_mov_b32_e32 v113, v96
	v_mov_b32_e32 v101, v97
	v_mov_b32_e32 v96, v109
	v_mov_b32_e32 v109, v94
	v_mov_b32_e32 v97, v95
	v_mov_b32_e32 v94, v103
	v_mov_b32_e32 v103, v90
	v_mov_b32_e32 v95, v91
	v_mov_b32_e32 v90, v99
	v_mov_b32_e32 v99, v88
	v_mov_b32_e32 v91, v89
	v_mov_b32_e32 v88, v93
	v_mov_b32_e32 v93, v124
	v_mov_b32_e32 v89, v125

.LBB0_1355:
	s_or_b64 exec, exec, s[10:11]
	s_waitcnt lgkmcnt(0)
	s_barrier
	ds_read_b32 v2, v2 offset:256
	v_mov_b32_e32 v91, v6
	s_waitcnt lgkmcnt(0)
	ds_bpermute_b32 v90, v141, v2
	s_waitcnt lgkmcnt(0)
	v_add_f32_e32 v2, v2, v90
	ds_bpermute_b32 v90, v142, v2
	s_waitcnt lgkmcnt(0)
	v_add_f32_e32 v2, v2, v90
	ds_bpermute_b32 v90, v143, v2
	s_waitcnt lgkmcnt(0)
	v_add_f32_e32 v2, v2, v90
	s_nop 0
	v_readlane_b32 s1, v2, 0
	v_readlane_b32 s16, v2, 1
	v_readlane_b32 s15, v2, 2
	v_readlane_b32 s14, v2, 3
	v_readlane_b32 s13, v2, 4
	v_readlane_b32 s12, v2, 5
	v_readlane_b32 s11, v2, 6
	v_readlane_b32 s10, v2, 7
	v_fma_f32 v2, s1, v206, v203
	v_cmp_gt_f32_e32 vcc, s2, v2
	v_mul_f32_e32 v90, 0x4b800000, v2
	s_ashr_i32 s1, s0, 31
	v_cndmask_b32_e32 v2, v2, v90, vcc
	v_rsq_f32_e32 v2, v2
	s_lshl_b64 s[18:19], s[0:1], 12
	v_lshl_add_u64 v[102:103], v[28:29], 0, s[18:19]
	v_mul_f32_e32 v90, 0x45800000, v2
	v_cndmask_b32_e32 v2, v2, v90, vcc
	v_pk_mul_f32 v[100:101], v[112:113], v[2:3] op_sel_hi:[1,0]
	v_mov_b32_e32 v90, v4
	v_pk_fma_f32 v[104:105], v[54:55], v[100:101], v[90:91]
	v_pk_mul_f32 v[106:107], v[110:111], v[2:3] op_sel_hi:[1,0]
	v_mov_b32_e32 v100, v5
	v_mov_b32_e32 v101, v7
	v_pk_fma_f32 v[106:107], v[72:73], v[106:107], v[100:101]
	v_and_b32_sdwa v2, v105, v202 dst_sel:DWORD dst_unused:UNUSED_PAD src0_sel:WORD_1 src1_sel:DWORD
	v_and_b32_sdwa v108, v104, v202 dst_sel:DWORD dst_unused:UNUSED_PAD src0_sel:WORD_1 src1_sel:DWORD
	v_add3_u32 v104, v104, v108, s5
	v_add3_u32 v2, v105, v2, s5
	v_and_b32_sdwa v105, v107, v202 dst_sel:DWORD dst_unused:UNUSED_PAD src0_sel:WORD_1 src1_sel:DWORD
	v_and_b32_sdwa v108, v106, v202 dst_sel:DWORD dst_unused:UNUSED_PAD src0_sel:WORD_1 src1_sel:DWORD
	v_add3_u32 v105, v107, v105, s5
	v_add3_u32 v106, v106, v108, s5
	v_and_b32_e32 v105, 0xffff0000, v105
	v_and_b32_e32 v106, 0xffff0000, v106
	v_or_b32_sdwa v105, v105, v2 dst_sel:DWORD dst_unused:UNUSED_PAD src0_sel:DWORD src1_sel:WORD_1
	v_or_b32_sdwa v104, v106, v104 dst_sel:DWORD dst_unused:UNUSED_PAD src0_sel:DWORD src1_sel:WORD_1
	v_fma_f32 v2, s16, v206, v203
	global_store_dwordx2 v[102:103], v[104:105], off
	v_cmp_gt_f32_e32 vcc, s2, v2
	v_mul_f32_e32 v102, 0x4b800000, v2
	s_add_i32 s16, s0, 1
	v_cndmask_b32_e32 v2, v2, v102, vcc
	v_rsq_f32_e32 v2, v2
	s_ashr_i32 s17, s16, 31
	s_lshl_b64 s[16:17], s[16:17], 12
	v_mul_f32_e32 v102, 0x45800000, v2
	v_cndmask_b32_e32 v2, v2, v102, vcc
	v_pk_mul_f32 v[98:99], v[98:99], v[2:3] op_sel_hi:[1,0]
	v_pk_mul_f32 v[96:97], v[96:97], v[2:3] op_sel_hi:[1,0]
	v_pk_fma_f32 v[98:99], v[54:55], v[98:99], v[90:91]
	v_pk_fma_f32 v[96:97], v[72:73], v[96:97], v[100:101]
	v_and_b32_sdwa v2, v99, v202 dst_sel:DWORD dst_unused:UNUSED_PAD src0_sel:WORD_1 src1_sel:DWORD
	v_and_b32_sdwa v104, v98, v202 dst_sel:DWORD dst_unused:UNUSED_PAD src0_sel:WORD_1 src1_sel:DWORD
	v_add3_u32 v98, v98, v104, s5
	v_add3_u32 v2, v99, v2, s5
	v_and_b32_sdwa v99, v97, v202 dst_sel:DWORD dst_unused:UNUSED_PAD src0_sel:WORD_1 src1_sel:DWORD
	v_and_b32_sdwa v104, v96, v202 dst_sel:DWORD dst_unused:UNUSED_PAD src0_sel:WORD_1 src1_sel:DWORD
	v_add3_u32 v97, v97, v99, s5
	v_add3_u32 v96, v96, v104, s5
	v_and_b32_e32 v97, 0xffff0000, v97
	v_and_b32_e32 v96, 0xffff0000, v96
	v_lshl_add_u64 v[102:103], v[28:29], 0, s[16:17]
	v_or_b32_sdwa v97, v97, v2 dst_sel:DWORD dst_unused:UNUSED_PAD src0_sel:DWORD src1_sel:WORD_1
	v_or_b32_sdwa v96, v96, v98 dst_sel:DWORD dst_unused:UNUSED_PAD src0_sel:DWORD src1_sel:WORD_1
	v_fma_f32 v2, s15, v206, v203
	global_store_dwordx2 v[102:103], v[96:97], off
	v_cmp_gt_f32_e32 vcc, s2, v2
	v_mul_f32_e32 v96, 0x4b800000, v2
	s_add_i32 s16, s0, 2
	v_cndmask_b32_e32 v2, v2, v96, vcc
	v_rsq_f32_e32 v2, v2
	s_ashr_i32 s17, s16, 31
	s_lshl_b64 s[16:17], s[16:17], 12
	v_mul_f32_e32 v96, 0x45800000, v2
	v_cndmask_b32_e32 v2, v2, v96, vcc
	v_pk_mul_f32 v[94:95], v[94:95], v[2:3] op_sel_hi:[1,0]
	v_pk_mul_f32 v[92:93], v[92:93], v[2:3] op_sel_hi:[1,0]
	v_pk_fma_f32 v[94:95], v[54:55], v[94:95], v[90:91]
	v_pk_fma_f32 v[92:93], v[72:73], v[92:93], v[100:101]
	v_and_b32_sdwa v2, v95, v202 dst_sel:DWORD dst_unused:UNUSED_PAD src0_sel:WORD_1 src1_sel:DWORD
	v_and_b32_sdwa v98, v94, v202 dst_sel:DWORD dst_unused:UNUSED_PAD src0_sel:WORD_1 src1_sel:DWORD
	v_add3_u32 v94, v94, v98, s5
	v_add3_u32 v2, v95, v2, s5
	v_and_b32_sdwa v95, v93, v202 dst_sel:DWORD dst_unused:UNUSED_PAD src0_sel:WORD_1 src1_sel:DWORD
	v_and_b32_sdwa v98, v92, v202 dst_sel:DWORD dst_unused:UNUSED_PAD src0_sel:WORD_1 src1_sel:DWORD
	v_add3_u32 v93, v93, v95, s5
	v_add3_u32 v92, v92, v98, s5
	v_and_b32_e32 v93, 0xffff0000, v93
	v_and_b32_e32 v92, 0xffff0000, v92
	v_lshl_add_u64 v[96:97], v[28:29], 0, s[16:17]
	v_or_b32_sdwa v93, v93, v2 dst_sel:DWORD dst_unused:UNUSED_PAD src0_sel:DWORD src1_sel:WORD_1
	v_or_b32_sdwa v92, v92, v94 dst_sel:DWORD dst_unused:UNUSED_PAD src0_sel:DWORD src1_sel:WORD_1
	v_fma_f32 v2, s14, v206, v203
	global_store_dwordx2 v[96:97], v[92:93], off
	v_cmp_gt_f32_e32 vcc, s2, v2
	v_mul_f32_e32 v92, 0x4b800000, v2
	s_add_i32 s14, s0, 3
	v_cndmask_b32_e32 v2, v2, v92, vcc
	v_rsq_f32_e32 v2, v2
	s_ashr_i32 s15, s14, 31
	s_lshl_b64 s[14:15], s[14:15], 12
	v_mul_f32_e32 v92, 0x45800000, v2
	v_cndmask_b32_e32 v2, v2, v92, vcc
	v_pk_mul_f32 v[88:89], v[88:89], v[2:3] op_sel_hi:[1,0]
	v_pk_mul_f32 v[86:87], v[86:87], v[2:3] op_sel_hi:[1,0]
	v_pk_fma_f32 v[88:89], v[54:55], v[88:89], v[90:91]
	v_pk_fma_f32 v[86:87], v[72:73], v[86:87], v[100:101]
	v_and_b32_sdwa v2, v89, v202 dst_sel:DWORD dst_unused:UNUSED_PAD src0_sel:WORD_1 src1_sel:DWORD
	v_and_b32_sdwa v94, v88, v202 dst_sel:DWORD dst_unused:UNUSED_PAD src0_sel:WORD_1 src1_sel:DWORD
	v_add3_u32 v88, v88, v94, s5
	v_add3_u32 v2, v89, v2, s5
	v_and_b32_sdwa v89, v87, v202 dst_sel:DWORD dst_unused:UNUSED_PAD src0_sel:WORD_1 src1_sel:DWORD
	v_and_b32_sdwa v94, v86, v202 dst_sel:DWORD dst_unused:UNUSED_PAD src0_sel:WORD_1 src1_sel:DWORD
	v_add3_u32 v87, v87, v89, s5
	v_add3_u32 v86, v86, v94, s5
	v_and_b32_e32 v87, 0xffff0000, v87
	v_and_b32_e32 v86, 0xffff0000, v86
	v_lshl_add_u64 v[92:93], v[28:29], 0, s[14:15]
	v_or_b32_sdwa v87, v87, v2 dst_sel:DWORD dst_unused:UNUSED_PAD src0_sel:DWORD src1_sel:WORD_1
	v_or_b32_sdwa v86, v86, v88 dst_sel:DWORD dst_unused:UNUSED_PAD src0_sel:DWORD src1_sel:WORD_1
	v_fma_f32 v2, s13, v206, v203
	global_store_dwordx2 v[92:93], v[86:87], off
	v_cmp_gt_f32_e32 vcc, s2, v2
	v_mul_f32_e32 v86, 0x4b800000, v2
	s_add_i32 s14, s0, 4
	v_cndmask_b32_e32 v2, v2, v86, vcc
	v_rsq_f32_e32 v2, v2
	s_ashr_i32 s15, s14, 31
	s_lshl_b64 s[14:15], s[14:15], 12
	v_mul_f32_e32 v86, 0x45800000, v2
	v_cndmask_b32_e32 v2, v2, v86, vcc
	v_pk_mul_f32 v[84:85], v[84:85], v[2:3] op_sel_hi:[1,0]
	v_pk_mul_f32 v[82:83], v[82:83], v[2:3] op_sel_hi:[1,0]
	v_pk_fma_f32 v[84:85], v[54:55], v[84:85], v[90:91]
	v_pk_fma_f32 v[82:83], v[72:73], v[82:83], v[100:101]
	v_and_b32_sdwa v2, v85, v202 dst_sel:DWORD dst_unused:UNUSED_PAD src0_sel:WORD_1 src1_sel:DWORD
	v_and_b32_sdwa v88, v84, v202 dst_sel:DWORD dst_unused:UNUSED_PAD src0_sel:WORD_1 src1_sel:DWORD
	v_add3_u32 v84, v84, v88, s5
	v_add3_u32 v2, v85, v2, s5
	v_and_b32_sdwa v85, v83, v202 dst_sel:DWORD dst_unused:UNUSED_PAD src0_sel:WORD_1 src1_sel:DWORD
	v_and_b32_sdwa v88, v82, v202 dst_sel:DWORD dst_unused:UNUSED_PAD src0_sel:WORD_1 src1_sel:DWORD
	v_add3_u32 v83, v83, v85, s5
	v_add3_u32 v82, v82, v88, s5
	v_and_b32_e32 v83, 0xffff0000, v83
	v_and_b32_e32 v82, 0xffff0000, v82
	v_lshl_add_u64 v[86:87], v[28:29], 0, s[14:15]
	v_or_b32_sdwa v83, v83, v2 dst_sel:DWORD dst_unused:UNUSED_PAD src0_sel:DWORD src1_sel:WORD_1
	v_or_b32_sdwa v82, v82, v84 dst_sel:DWORD dst_unused:UNUSED_PAD src0_sel:DWORD src1_sel:WORD_1
	v_fma_f32 v2, s12, v206, v203
	global_store_dwordx2 v[86:87], v[82:83], off
	v_cmp_gt_f32_e32 vcc, s2, v2
	v_mul_f32_e32 v82, 0x4b800000, v2
	s_add_i32 s12, s0, 5
	v_cndmask_b32_e32 v2, v2, v82, vcc
	v_rsq_f32_e32 v2, v2
	s_ashr_i32 s13, s12, 31
	s_lshl_b64 s[12:13], s[12:13], 12
	v_mul_f32_e32 v82, 0x45800000, v2
	v_cndmask_b32_e32 v2, v2, v82, vcc
	v_pk_mul_f32 v[80:81], v[80:81], v[2:3] op_sel_hi:[1,0]
	v_pk_mul_f32 v[78:79], v[78:79], v[2:3] op_sel_hi:[1,0]
	v_pk_fma_f32 v[80:81], v[54:55], v[80:81], v[90:91]
	v_pk_fma_f32 v[78:79], v[72:73], v[78:79], v[100:101]
	v_and_b32_sdwa v2, v81, v202 dst_sel:DWORD dst_unused:UNUSED_PAD src0_sel:WORD_1 src1_sel:DWORD
	v_and_b32_sdwa v84, v80, v202 dst_sel:DWORD dst_unused:UNUSED_PAD src0_sel:WORD_1 src1_sel:DWORD
	v_add3_u32 v80, v80, v84, s5
	v_add3_u32 v2, v81, v2, s5
	v_and_b32_sdwa v81, v79, v202 dst_sel:DWORD dst_unused:UNUSED_PAD src0_sel:WORD_1 src1_sel:DWORD
	v_and_b32_sdwa v84, v78, v202 dst_sel:DWORD dst_unused:UNUSED_PAD src0_sel:WORD_1 src1_sel:DWORD
	v_add3_u32 v79, v79, v81, s5
	v_add3_u32 v78, v78, v84, s5
	v_and_b32_e32 v79, 0xffff0000, v79
	v_and_b32_e32 v78, 0xffff0000, v78
	v_lshl_add_u64 v[82:83], v[28:29], 0, s[12:13]
	v_or_b32_sdwa v79, v79, v2 dst_sel:DWORD dst_unused:UNUSED_PAD src0_sel:DWORD src1_sel:WORD_1
	v_or_b32_sdwa v78, v78, v80 dst_sel:DWORD dst_unused:UNUSED_PAD src0_sel:DWORD src1_sel:WORD_1
	v_fma_f32 v2, s11, v206, v203
	global_store_dwordx2 v[82:83], v[78:79], off
	v_cmp_gt_f32_e32 vcc, s2, v2
	v_mul_f32_e32 v78, 0x4b800000, v2
	s_add_i32 s12, s0, 6
	v_cndmask_b32_e32 v2, v2, v78, vcc
	v_rsq_f32_e32 v2, v2
	s_ashr_i32 s13, s12, 31
	s_lshl_b64 s[12:13], s[12:13], 12
	v_mul_f32_e32 v78, 0x45800000, v2
	v_cndmask_b32_e32 v2, v2, v78, vcc
	v_pk_mul_f32 v[76:77], v[76:77], v[2:3] op_sel_hi:[1,0]
	v_pk_mul_f32 v[74:75], v[74:75], v[2:3] op_sel_hi:[1,0]
	v_pk_fma_f32 v[76:77], v[54:55], v[76:77], v[90:91]
	v_pk_fma_f32 v[74:75], v[72:73], v[74:75], v[100:101]
	v_and_b32_sdwa v2, v77, v202 dst_sel:DWORD dst_unused:UNUSED_PAD src0_sel:WORD_1 src1_sel:DWORD
	v_and_b32_sdwa v80, v76, v202 dst_sel:DWORD dst_unused:UNUSED_PAD src0_sel:WORD_1 src1_sel:DWORD
	v_add3_u32 v76, v76, v80, s5
	v_add3_u32 v2, v77, v2, s5
	v_and_b32_sdwa v77, v75, v202 dst_sel:DWORD dst_unused:UNUSED_PAD src0_sel:WORD_1 src1_sel:DWORD
	v_and_b32_sdwa v80, v74, v202 dst_sel:DWORD dst_unused:UNUSED_PAD src0_sel:WORD_1 src1_sel:DWORD
	v_add3_u32 v75, v75, v77, s5
	v_add3_u32 v74, v74, v80, s5
	v_and_b32_e32 v75, 0xffff0000, v75
	v_and_b32_e32 v74, 0xffff0000, v74
	v_lshl_add_u64 v[78:79], v[28:29], 0, s[12:13]
	v_or_b32_sdwa v75, v75, v2 dst_sel:DWORD dst_unused:UNUSED_PAD src0_sel:DWORD src1_sel:WORD_1
	v_or_b32_sdwa v74, v74, v76 dst_sel:DWORD dst_unused:UNUSED_PAD src0_sel:DWORD src1_sel:WORD_1
	v_fma_f32 v2, s10, v206, v203
	global_store_dwordx2 v[78:79], v[74:75], off
	v_cmp_gt_f32_e32 vcc, s2, v2
	v_mul_f32_e32 v74, 0x4b800000, v2
	s_add_i32 s10, s0, 7
	v_cndmask_b32_e32 v2, v2, v74, vcc
	v_rsq_f32_e32 v2, v2
	s_ashr_i32 s11, s10, 31
	s_lshl_b64 s[10:11], s[10:11], 12
	v_mul_f32_e32 v74, 0x45800000, v2
	v_cndmask_b32_e32 v2, v2, v74, vcc
	v_pk_mul_f32 v[14:15], v[14:15], v[2:3] op_sel_hi:[1,0]
	v_pk_mul_f32 v[12:13], v[12:13], v[2:3] op_sel_hi:[1,0]
	v_pk_fma_f32 v[14:15], v[54:55], v[14:15], v[90:91]
	v_pk_fma_f32 v[12:13], v[72:73], v[12:13], v[100:101]
	v_and_b32_sdwa v2, v15, v202 dst_sel:DWORD dst_unused:UNUSED_PAD src0_sel:WORD_1 src1_sel:DWORD
	v_and_b32_sdwa v76, v14, v202 dst_sel:DWORD dst_unused:UNUSED_PAD src0_sel:WORD_1 src1_sel:DWORD
	v_add3_u32 v14, v14, v76, s5
	v_add3_u32 v2, v15, v2, s5
	v_and_b32_sdwa v15, v13, v202 dst_sel:DWORD dst_unused:UNUSED_PAD src0_sel:WORD_1 src1_sel:DWORD
	v_and_b32_sdwa v76, v12, v202 dst_sel:DWORD dst_unused:UNUSED_PAD src0_sel:WORD_1 src1_sel:DWORD
	v_add3_u32 v13, v13, v15, s5
	v_add3_u32 v12, v12, v76, s5
	v_and_b32_e32 v13, 0xffff0000, v13
	v_and_b32_e32 v12, 0xffff0000, v12
	v_lshl_add_u64 v[74:75], v[28:29], 0, s[10:11]
	v_or_b32_sdwa v13, v13, v2 dst_sel:DWORD dst_unused:UNUSED_PAD src0_sel:DWORD src1_sel:WORD_1
	v_or_b32_sdwa v12, v12, v14 dst_sel:DWORD dst_unused:UNUSED_PAD src0_sel:DWORD src1_sel:WORD_1
	global_store_dwordx2 v[74:75], v[12:13], off
.LBB0_1356:
	v_readlane_b32 s1, v250, 47
	s_addk_i32 s34, 0x80
	s_add_i32 s0, s0, s1
	s_andn2_b64 vcc, exec, s[8:9]
	v_mov_b64_e32 v[74:75], v[46:47]
	v_mov_b64_e32 v[76:77], v[48:49]
	v_mov_b64_e32 v[78:79], v[50:51]
	v_mov_b64_e32 v[80:81], v[52:53]
	v_mov_b64_e32 v[82:83], v[38:39]
	v_mov_b64_e32 v[84:85], v[40:41]
	v_mov_b64_e32 v[86:87], v[42:43]
	v_mov_b64_e32 v[88:89], v[44:45]
	v_mov_b64_e32 v[94:95], v[64:65]
	v_mov_b64_e32 v[90:91], v[66:67]
	v_mov_b64_e32 v[96:97], v[68:69]
	v_mov_b64_e32 v[98:99], v[70:71]
	v_mov_b64_e32 v[100:101], v[56:57]
	v_mov_b64_e32 v[92:93], v[58:59]
	v_mov_b64_e32 v[102:103], v[60:61]
	v_mov_b64_e32 v[104:105], v[62:63]
	s_mov_b32 s1, s46
	s_cbranch_vccz .LBB0_1374

.LBB0_1363:
	v_readlane_b32 s2, v250, 19
	s_cmpk_lt_i32 s1, 0x400
	v_readlane_b32 s3, v250, 20
	s_cselect_b64 s[10:11], -1, 0
	s_xor_b64 s[12:13], s[2:3], -1
	s_or_b64 s[10:11], s[12:13], s[10:11]
	s_waitcnt vmcnt(7)
	v_lshlrev_b32_e32 v112, 16, v104
	v_and_b32_e32 v110, 0xffff0000, v104
	v_lshlrev_b32_e32 v113, 16, v105
	v_and_b32_e32 v111, 0xffff0000, v105
	s_waitcnt vmcnt(6)
	v_lshlrev_b32_e32 v122, 16, v102
	v_and_b32_e32 v114, 0xffff0000, v102
	v_lshlrev_b32_e32 v123, 16, v103
	v_and_b32_e32 v115, 0xffff0000, v103
	s_waitcnt vmcnt(5)
	v_lshlrev_b32_e32 v120, 16, v92
	v_and_b32_e32 v92, 0xffff0000, v92
	v_lshlrev_b32_e32 v121, 16, v93
	v_and_b32_e32 v93, 0xffff0000, v93
	s_waitcnt vmcnt(4)
	v_lshlrev_b32_e32 v118, 16, v100
	v_and_b32_e32 v106, 0xffff0000, v100
	v_lshlrev_b32_e32 v119, 16, v101
	v_and_b32_e32 v107, 0xffff0000, v101
	s_waitcnt vmcnt(3)
	v_lshlrev_b32_e32 v116, 16, v98
	v_and_b32_e32 v102, 0xffff0000, v98
	v_lshlrev_b32_e32 v117, 16, v99
	v_and_b32_e32 v103, 0xffff0000, v99
	s_waitcnt vmcnt(2)
	v_lshlrev_b32_e32 v108, 16, v96
	v_and_b32_e32 v100, 0xffff0000, v96
	v_lshlrev_b32_e32 v109, 16, v97
	v_and_b32_e32 v101, 0xffff0000, v97
	s_waitcnt vmcnt(1)
	v_lshlrev_b32_e32 v104, 16, v90
	v_and_b32_e32 v14, 0xffff0000, v90
	v_lshlrev_b32_e32 v105, 16, v91
	v_and_b32_e32 v15, 0xffff0000, v91
	s_waitcnt vmcnt(0)
	v_lshlrev_b32_e32 v90, 16, v94
	v_and_b32_e32 v12, 0xffff0000, v94
	v_lshlrev_b32_e32 v91, 16, v95
	v_and_b32_e32 v13, 0xffff0000, v95
	s_and_b64 vcc, exec, s[10:11]
	s_cbranch_vccnz .LBB0_1365
	s_add_i32 s28, s0, 1
	s_lshl_b64 s[12:13], s[28:29], 12
	s_add_i32 s28, s0, 2
	s_lshl_b64 s[14:15], s[28:29], 12
	s_add_i32 s28, s0, 3
	s_lshl_b64 s[18:19], s[28:29], 12
	s_add_i32 s28, s0, 4
	s_lshl_b64 s[16:17], s[28:29], 12
	s_add_i32 s28, s0, 5
	s_lshl_b64 s[20:21], s[28:29], 12
	s_add_i32 s28, s0, 6
	s_mov_b32 s1, s29
	s_lshl_b64 s[24:25], s[28:29], 12
	s_add_i32 s28, s0, 7
	s_lshl_b64 s[10:11], s[0:1], 12
	s_lshl_b64 s[26:27], s[28:29], 12
	v_lshl_add_u64 v[94:95], v[30:31], 0, s[10:11]
	v_lshl_add_u64 v[132:133], v[30:31], 0, s[24:25]
	v_mov_b32_e32 v150, v108
	v_mov_b32_e32 v151, v100
	v_lshl_add_u64 v[152:153], v[32:33], 0, s[20:21]
	v_mov_b32_e32 v100, v109
	v_mov_b32_e32 v108, v104
	v_mov_b32_e32 v109, v14
	v_mov_b32_e32 v14, v105
	v_lshl_add_u64 v[104:105], v[32:33], 0, s[26:27]
	global_load_dwordx2 v[98:99], v[94:95], off
	v_lshl_add_u64 v[134:135], v[30:31], 0, s[26:27]
	global_load_dwordx2 v[132:133], v[132:133], off
	v_mov_b32_e32 v144, v118
	v_mov_b32_e32 v145, v106
	v_mov_b32_e32 v106, v119
	v_mov_b32_e32 v118, v116
	v_mov_b32_e32 v119, v102
	v_mov_b32_e32 v102, v117
	v_lshl_add_u64 v[116:117], v[32:33], 0, s[16:17]
	global_load_dwordx2 v[152:153], v[152:153], off
	v_lshl_add_u64 v[154:155], v[32:33], 0, s[24:25]
	global_load_dwordx2 v[104:105], v[104:105], off
	v_lshl_add_u64 v[94:95], v[30:31], 0, s[12:13]
	global_load_dwordx2 v[124:125], v[94:95], off
	v_lshl_add_u64 v[96:97], v[30:31], 0, s[18:19]
	v_lshl_add_u64 v[128:129], v[30:31], 0, s[16:17]
	v_lshl_add_u64 v[130:131], v[30:31], 0, s[20:21]
	global_load_dwordx2 v[134:135], v[134:135], off
	v_lshl_add_u64 v[146:147], v[32:33], 0, s[14:15]
	v_lshl_add_u64 v[148:149], v[32:33], 0, s[18:19]
	global_load_dwordx2 v[154:155], v[154:155], off
	v_lshl_add_u64 v[136:137], v[32:33], 0, s[10:11]
	global_load_dwordx2 v[116:117], v[116:117], off
	v_lshl_add_u64 v[94:95], v[30:31], 0, s[14:15]
	global_load_dwordx2 v[126:127], v[94:95], off
	v_lshl_add_u64 v[158:159], v[34:35], 0, s[10:11]
	global_load_dwordx2 v[128:129], v[128:129], off
	v_mov_b32_e32 v156, v90
	global_load_dwordx2 v[130:131], v[130:131], off
	v_mov_b32_e32 v157, v12
	global_load_dwordx2 v[146:147], v[146:147], off
	v_mov_b32_e32 v94, v112
	v_mov_b32_e32 v95, v110
	v_mov_b32_e32 v110, v113
	global_load_dwordx2 v[112:113], v[96:97], off
	v_mov_b32_e32 v12, v91
	global_load_dwordx2 v[148:149], v[148:149], off
	v_mov_b32_e32 v96, v122
	v_mov_b32_e32 v97, v114
	v_mov_b32_e32 v114, v123
	v_mov_b32_e32 v122, v120
	v_mov_b32_e32 v123, v92
	v_mov_b32_e32 v92, v121
	v_lshl_add_u64 v[120:121], v[32:33], 0, s[12:13]
	global_load_dwordx2 v[136:137], v[136:137], off
	v_lshl_add_u64 v[90:91], v[34:35], 0, s[12:13]
	global_load_dwordx2 v[158:159], v[158:159], off
	v_lshl_add_u64 v[160:161], v[34:35], 0, s[14:15]
	global_load_dwordx2 v[120:121], v[120:121], off
	v_lshl_add_u64 v[162:163], v[34:35], 0, s[18:19]
	v_lshl_add_u64 v[180:181], v[34:35], 0, s[16:17]
	v_lshl_add_u64 v[184:185], v[34:35], 0, s[20:21]
	v_lshl_add_u64 v[186:187], v[34:35], 0, s[24:25]
	v_lshl_add_u64 v[190:191], v[34:35], 0, s[26:27]
	global_load_dwordx2 v[90:91], v[90:91], off
	s_nop 0
	global_load_dwordx2 v[160:161], v[160:161], off
	s_waitcnt vmcnt(18)
	v_lshlrev_b32_e32 v164, 16, v98
	global_load_dwordx2 v[162:163], v[162:163], off
	v_and_b32_e32 v165, 0xffff0000, v98
	global_load_dwordx2 v[180:181], v[180:181], off
	v_lshlrev_b32_e32 v98, 16, v99
	global_load_dwordx2 v[184:185], v[184:185], off
	v_and_b32_e32 v99, 0xffff0000, v99
	global_load_dwordx2 v[186:187], v[186:187], off
	s_waitcnt vmcnt(21)
	v_lshlrev_b32_e32 v196, 16, v132
	global_load_dwordx2 v[190:191], v[190:191], off
	v_and_b32_e32 v197, 0xffff0000, v132
	v_lshlrev_b32_e32 v132, 16, v133
	v_and_b32_e32 v133, 0xffff0000, v133
	s_waitcnt vmcnt(21)
	v_lshlrev_b32_e32 v218, 16, v152
	s_waitcnt vmcnt(19)
	v_lshlrev_b32_e32 v166, 16, v124
	v_and_b32_e32 v167, 0xffff0000, v124
	v_lshlrev_b32_e32 v124, 16, v125
	v_and_b32_e32 v125, 0xffff0000, v125
	s_waitcnt vmcnt(18)
	v_lshlrev_b32_e32 v198, 16, v134
	v_and_b32_e32 v199, 0xffff0000, v134
	v_lshlrev_b32_e32 v134, 16, v135
	v_and_b32_e32 v135, 0xffff0000, v135
	v_and_b32_e32 v219, 0xffff0000, v152
	s_waitcnt vmcnt(16)
	v_lshlrev_b32_e32 v216, 16, v116
	v_and_b32_e32 v217, 0xffff0000, v116
	s_waitcnt vmcnt(15)
	v_lshlrev_b32_e32 v182, 16, v126
	v_and_b32_e32 v183, 0xffff0000, v126
	v_lshlrev_b32_e32 v126, 16, v127
	v_and_b32_e32 v127, 0xffff0000, v127
	s_waitcnt vmcnt(14)
	v_lshlrev_b32_e32 v192, 16, v128
	v_and_b32_e32 v193, 0xffff0000, v128
	v_lshlrev_b32_e32 v128, 16, v129
	v_and_b32_e32 v129, 0xffff0000, v129
	s_waitcnt vmcnt(13)
	v_lshlrev_b32_e32 v194, 16, v130
	v_and_b32_e32 v195, 0xffff0000, v130
	s_waitcnt vmcnt(11)
	v_lshlrev_b32_e32 v188, 16, v112
	v_and_b32_e32 v189, 0xffff0000, v112
	v_lshlrev_b32_e32 v112, 16, v113
	v_and_b32_e32 v113, 0xffff0000, v113
	v_lshlrev_b32_e32 v130, 16, v131
	v_and_b32_e32 v131, 0xffff0000, v131
	v_lshlrev_b32_e32 v212, 16, v146
	v_and_b32_e32 v213, 0xffff0000, v146
	v_lshlrev_b32_e32 v146, 16, v147
	v_and_b32_e32 v147, 0xffff0000, v147
	s_waitcnt vmcnt(9)
	v_lshlrev_b32_e32 v208, 16, v136
	v_and_b32_e32 v209, 0xffff0000, v136
	v_lshlrev_b32_e32 v136, 16, v137
	v_and_b32_e32 v137, 0xffff0000, v137
	s_waitcnt vmcnt(7)
	v_lshlrev_b32_e32 v210, 16, v120
	v_and_b32_e32 v211, 0xffff0000, v120
	v_lshlrev_b32_e32 v120, 16, v121
	v_and_b32_e32 v121, 0xffff0000, v121
	v_lshlrev_b32_e32 v214, 16, v148
	v_and_b32_e32 v215, 0xffff0000, v148
	v_lshlrev_b32_e32 v148, 16, v149
	v_and_b32_e32 v149, 0xffff0000, v149
	v_lshlrev_b32_e32 v116, 16, v117
	v_and_b32_e32 v117, 0xffff0000, v117
	v_lshlrev_b32_e32 v152, 16, v153
	v_and_b32_e32 v153, 0xffff0000, v153
	v_lshlrev_b32_e32 v220, 16, v154
	v_and_b32_e32 v221, 0xffff0000, v154
	v_lshlrev_b32_e32 v154, 16, v155
	v_and_b32_e32 v155, 0xffff0000, v155
	v_lshlrev_b32_e32 v222, 16, v104
	v_and_b32_e32 v223, 0xffff0000, v104
	v_lshlrev_b32_e32 v104, 16, v105
	v_and_b32_e32 v105, 0xffff0000, v105
	v_pk_add_f32 v[12:13], v[12:13], v[134:135]
	v_pk_add_f32 v[134:135], v[156:157], v[198:199]
	v_pk_add_f32 v[14:15], v[14:15], v[132:133]
	v_pk_add_f32 v[108:109], v[108:109], v[196:197]
	v_pk_add_f32 v[100:101], v[100:101], v[130:131]
	v_pk_add_f32 v[130:131], v[150:151], v[194:195]
	v_pk_add_f32 v[102:103], v[102:103], v[128:129]
	v_pk_add_f32 v[118:119], v[118:119], v[192:193]
	v_pk_add_f32 v[106:107], v[106:107], v[112:113]
	v_pk_add_f32 v[112:113], v[144:145], v[188:189]
	v_pk_add_f32 v[92:93], v[92:93], v[126:127]
	v_pk_add_f32 v[122:123], v[122:123], v[182:183]
	v_pk_add_f32 v[114:115], v[114:115], v[124:125]
	v_pk_add_f32 v[96:97], v[96:97], v[166:167]
	v_pk_add_f32 v[98:99], v[110:111], v[98:99]
	v_pk_add_f32 v[94:95], v[94:95], v[164:165]
	v_lshlrev_b32_e32 v224, 16, v158
	v_and_b32_e32 v225, 0xffff0000, v158
	v_lshlrev_b32_e32 v158, 16, v159
	v_and_b32_e32 v159, 0xffff0000, v159
	s_waitcnt vmcnt(6)
	v_lshlrev_b32_e32 v226, 16, v90
	v_and_b32_e32 v227, 0xffff0000, v90
	v_lshlrev_b32_e32 v228, 16, v91
	v_and_b32_e32 v229, 0xffff0000, v91
	s_waitcnt vmcnt(5)
	v_lshlrev_b32_e32 v230, 16, v160
	v_and_b32_e32 v231, 0xffff0000, v160
	v_lshlrev_b32_e32 v160, 16, v161
	v_and_b32_e32 v161, 0xffff0000, v161
	s_waitcnt vmcnt(4)
	v_lshlrev_b32_e32 v232, 16, v162
	v_and_b32_e32 v233, 0xffff0000, v162
	v_lshlrev_b32_e32 v162, 16, v163
	v_and_b32_e32 v163, 0xffff0000, v163
	s_waitcnt vmcnt(3)
	v_lshlrev_b32_e32 v234, 16, v180
	v_and_b32_e32 v235, 0xffff0000, v180
	v_lshlrev_b32_e32 v180, 16, v181
	v_and_b32_e32 v181, 0xffff0000, v181
	s_waitcnt vmcnt(2)
	v_lshlrev_b32_e32 v236, 16, v184
	v_and_b32_e32 v237, 0xffff0000, v184
	v_lshlrev_b32_e32 v184, 16, v185
	v_and_b32_e32 v185, 0xffff0000, v185
	s_waitcnt vmcnt(1)
	v_lshlrev_b32_e32 v238, 16, v186
	v_and_b32_e32 v239, 0xffff0000, v186
	v_lshlrev_b32_e32 v186, 16, v187
	v_and_b32_e32 v187, 0xffff0000, v187
	s_waitcnt vmcnt(0)
	v_lshlrev_b32_e32 v90, 16, v190
	v_and_b32_e32 v91, 0xffff0000, v190
	v_lshlrev_b32_e32 v190, 16, v191
	v_and_b32_e32 v191, 0xffff0000, v191
	v_pk_add_f32 v[94:95], v[94:95], v[208:209]
	v_pk_add_f32 v[98:99], v[98:99], v[136:137]
	v_pk_add_f32 v[96:97], v[96:97], v[210:211]
	v_pk_add_f32 v[110:111], v[114:115], v[120:121]
	v_pk_add_f32 v[114:115], v[122:123], v[212:213]
	v_pk_add_f32 v[92:93], v[92:93], v[146:147]
	v_pk_add_f32 v[112:113], v[112:113], v[214:215]
	v_pk_add_f32 v[106:107], v[106:107], v[148:149]
	v_pk_add_f32 v[118:119], v[118:119], v[216:217]
	v_pk_add_f32 v[102:103], v[102:103], v[116:117]
	v_pk_add_f32 v[116:117], v[130:131], v[218:219]
	v_pk_add_f32 v[100:101], v[100:101], v[152:153]
	v_pk_add_f32 v[108:109], v[108:109], v[220:221]
	v_pk_add_f32 v[14:15], v[14:15], v[154:155]
	v_pk_add_f32 v[120:121], v[134:135], v[222:223]
	v_pk_add_f32 v[12:13], v[12:13], v[104:105]
	v_pk_add_f32 v[90:91], v[120:121], v[90:91]
	v_pk_add_f32 v[124:125], v[12:13], v[190:191]
	v_pk_add_f32 v[12:13], v[14:15], v[186:187]
	v_pk_add_f32 v[104:105], v[108:109], v[238:239]
	v_pk_add_f32 v[14:15], v[100:101], v[184:185]
	v_pk_add_f32 v[108:109], v[116:117], v[236:237]
	v_pk_add_f32 v[100:101], v[102:103], v[180:181]
	v_pk_add_f32 v[116:117], v[118:119], v[234:235]
	v_pk_add_f32 v[102:103], v[106:107], v[162:163]
	v_pk_add_f32 v[118:119], v[112:113], v[232:233]
	v_pk_add_f32 v[106:107], v[92:93], v[160:161]
	v_pk_add_f32 v[120:121], v[114:115], v[230:231]
	v_pk_add_f32 v[92:93], v[110:111], v[228:229]
	v_pk_add_f32 v[122:123], v[96:97], v[226:227]
	v_pk_add_f32 v[96:97], v[98:99], v[158:159]
	v_pk_add_f32 v[112:113], v[94:95], v[224:225]
	v_mov_b32_e32 v111, v97
	v_mov_b32_e32 v110, v113
	v_mov_b32_e32 v113, v96
	v_mov_b32_e32 v114, v123
	v_mov_b32_e32 v123, v92
	v_mov_b32_e32 v115, v93
	v_mov_b32_e32 v92, v121
	v_mov_b32_e32 v121, v106
	v_mov_b32_e32 v93, v107
	v_mov_b32_e32 v106, v119
	v_mov_b32_e32 v119, v102
	v_mov_b32_e32 v107, v103
	v_mov_b32_e32 v102, v117
	v_mov_b32_e32 v117, v100
	v_mov_b32_e32 v103, v101
	v_mov_b32_e32 v100, v109
	v_mov_b32_e32 v109, v14
	v_mov_b32_e32 v101, v15
	v_mov_b32_e32 v14, v105
	v_mov_b32_e32 v105, v12
	v_mov_b32_e32 v15, v13
	v_mov_b32_e32 v12, v91
	v_mov_b32_e32 v91, v124
	v_mov_b32_e32 v13, v125

.LBB0_1369:
	s_and_b64 vcc, exec, s[44:45]
	s_cbranch_vccnz .LBB0_1356
	s_branch .LBB0_1372

.LBB0_1371:
	s_ashr_i32 s1, s0, 31
	s_lshl_b64 s[10:11], s[0:1], 13
	v_lshl_add_u64 v[90:91], v[36:37], 0, s[10:11]
	v_mov_b32_e32 v100, v112
	v_mov_b32_e32 v101, v110
	v_mov_b32_e32 v102, v113
	v_mov_b32_e32 v103, v111
	v_add_co_u32_e32 v104, vcc, 0x2000, v90
	global_store_dwordx4 v[90:91], v[100:103], off
	s_nop 0
	v_addc_co_u32_e32 v105, vcc, 0, v91, vcc
	v_mov_b32_e32 v100, v98
	v_mov_b32_e32 v101, v96
	v_mov_b32_e32 v102, v99
	v_mov_b32_e32 v103, v97
	global_store_dwordx4 v[104:105], v[100:103], off
	v_add_co_u32_e32 v104, vcc, 0x4000, v90
	s_nop 0
	v_mov_b32_e32 v100, v94
	v_mov_b32_e32 v101, v92
	v_mov_b32_e32 v102, v95
	v_mov_b32_e32 v103, v93
	v_addc_co_u32_e32 v105, vcc, 0, v91, vcc
	global_store_dwordx4 v[104:105], v[100:103], off
	v_add_co_u32_e32 v104, vcc, 0x6000, v90
	s_nop 0
	v_mov_b32_e32 v100, v88
	v_mov_b32_e32 v101, v86
	v_mov_b32_e32 v102, v89
	v_mov_b32_e32 v103, v87
	v_addc_co_u32_e32 v105, vcc, 0, v91, vcc
	global_store_dwordx4 v[104:105], v[100:103], off
	v_add_co_u32_e32 v104, vcc, 0x8000, v90
	s_nop 0
	v_mov_b32_e32 v100, v84
	v_mov_b32_e32 v101, v82
	v_mov_b32_e32 v102, v85
	v_mov_b32_e32 v103, v83
	v_addc_co_u32_e32 v105, vcc, 0, v91, vcc
	global_store_dwordx4 v[104:105], v[100:103], off
	v_add_co_u32_e32 v104, vcc, 0xa000, v90
	s_nop 0
	v_mov_b32_e32 v100, v80
	v_mov_b32_e32 v101, v78
	v_mov_b32_e32 v102, v81
	v_mov_b32_e32 v103, v79
	v_addc_co_u32_e32 v105, vcc, 0, v91, vcc
	global_store_dwordx4 v[104:105], v[100:103], off
	v_add_co_u32_e32 v104, vcc, 0xc000, v90
	s_nop 0
	v_mov_b32_e32 v100, v76
	v_addc_co_u32_e32 v105, vcc, 0, v91, vcc
	v_mov_b32_e32 v101, v74
	v_mov_b32_e32 v102, v77
	v_mov_b32_e32 v103, v75
	v_add_co_u32_e32 v90, vcc, 0xe000, v90
	global_store_dwordx4 v[104:105], v[100:103], off
	s_nop 0
	v_addc_co_u32_e32 v91, vcc, 0, v91, vcc
	v_mov_b32_e32 v100, v14
	v_mov_b32_e32 v101, v12
	v_mov_b32_e32 v102, v15
	v_mov_b32_e32 v103, v13
	global_store_dwordx4 v[90:91], v[100:103], off
	s_and_b64 vcc, exec, s[44:45]
	s_cbranch_vccnz .LBB0_1356
